# accumulator zeroing per unit: 64x v_mov_b64 0 instead of 128x v_mov_b32 (on top of static-priority / MFMA-order / SGPR-base LDS-DMA version)
# baseline (speedup 1.0000x reference)
; template <class Epi, class Sched, bool ALIGN_EPI = false, bool SP2 = false>
; __device__ __forceinline__ void gemm_phase(PG8_LAS unsigned char* lds, const Gemm g, const Sched& S, const Epi& E) {
;     ...
;     f32x4 acc[2][2][4][2];
; #pragma unroll
;     for (int a = 0; a < 2; ++a)
; #pragma unroll
;         for (int b = 0; b < 2; ++b)
; #pragma unroll
;             for (int m = 0; m < 4; ++m)
; #pragma unroll
;                 for (int n = 0; n < 2; ++n) acc[a][b][m][n] = (f32x4){0.f, 0.f, 0.f, 0.f};
;     ...
;         for (int a = 0; a < 2; ++a)
; #pragma unroll
;             for (int b = 0; b < 2; ++b)
; #pragma unroll
;                 for (int m = 0; m < 4; ++m)
; #pragma unroll
;                     for (int n = 0; n < 2; ++n) acc[a][b][m][n] = (f32x4){0.f, 0.f, 0.f, 0.f};
.LBB0_191:
	s_ashr_i32 s19, s18, 31
	s_lshl_b64 s[26:27], s[18:19], 20
	s_add_u32 s26, s3, s26
	s_addc_u32 s27, s33, s27
	s_and_b64 s[34:35], s[4:5], exec
	s_cselect_b32 s19, s27, s67
	s_cselect_b32 s50, s26, s66
	s_ashr_i32 s17, s16, 31
	s_lshl_b64 s[34:35], s[16:17], 20
	s_add_u32 s34, s6, s34
	s_addc_u32 s35, s7, s35
	s_and_b64 s[52:53], s[4:5], exec
	s_cselect_b32 s17, s35, s69
	s_cselect_b32 s51, s34, s68
	s_add_u32 s66, s66, 0x80080
	s_addc_u32 s67, s67, 0
	s_add_u32 s52, s68, 0x100
	v_mov_b64_e32 v[0:1], 0
	v_mov_b64_e32 v[2:3], 0
	v_mov_b64_e32 v[4:5], 0
	v_mov_b64_e32 v[6:7], 0
	v_mov_b64_e32 v[8:9], 0
	v_mov_b64_e32 v[10:11], 0
	v_mov_b64_e32 v[12:13], 0
	v_mov_b64_e32 v[14:15], 0
	v_mov_b64_e32 v[16:17], 0
	v_mov_b64_e32 v[18:19], 0
	v_mov_b64_e32 v[20:21], 0
	v_mov_b64_e32 v[22:23], 0
	v_mov_b64_e32 v[24:25], 0
	v_mov_b64_e32 v[26:27], 0
	v_mov_b64_e32 v[28:29], 0
	v_mov_b64_e32 v[30:31], 0
	v_mov_b64_e32 v[32:33], 0
	v_mov_b64_e32 v[34:35], 0
	v_mov_b64_e32 v[36:37], 0
	v_mov_b64_e32 v[38:39], 0
	v_mov_b64_e32 v[40:41], 0
	v_mov_b64_e32 v[42:43], 0
	v_mov_b64_e32 v[44:45], 0
	v_mov_b64_e32 v[46:47], 0
	v_mov_b64_e32 v[48:49], 0
	v_mov_b64_e32 v[50:51], 0
	v_mov_b64_e32 v[52:53], 0
	v_mov_b64_e32 v[54:55], 0
	v_mov_b64_e32 v[56:57], 0
	v_mov_b64_e32 v[58:59], 0
	v_mov_b64_e32 v[60:61], 0
	v_mov_b64_e32 v[62:63], 0
	v_mov_b64_e32 v[64:65], 0
	v_mov_b64_e32 v[66:67], 0
	v_mov_b64_e32 v[68:69], 0
	v_mov_b64_e32 v[70:71], 0
	v_mov_b64_e32 v[72:73], 0
	v_mov_b64_e32 v[74:75], 0
	v_mov_b64_e32 v[76:77], 0
	v_mov_b64_e32 v[78:79], 0
	v_mov_b64_e32 v[80:81], 0
	v_mov_b64_e32 v[82:83], 0
	v_mov_b64_e32 v[84:85], 0
	v_mov_b64_e32 v[86:87], 0
	v_mov_b64_e32 v[88:89], 0
	v_mov_b64_e32 v[90:91], 0
	v_mov_b64_e32 v[92:93], 0
	v_mov_b64_e32 v[94:95], 0
	v_mov_b64_e32 v[96:97], 0
	v_mov_b64_e32 v[98:99], 0
	v_mov_b64_e32 v[100:101], 0
	v_mov_b64_e32 v[102:103], 0
	v_mov_b64_e32 v[104:105], 0
	v_mov_b64_e32 v[106:107], 0
	v_mov_b64_e32 v[108:109], 0
	v_mov_b64_e32 v[110:111], 0
	v_mov_b64_e32 v[112:113], 0
	v_mov_b64_e32 v[114:115], 0
	v_mov_b64_e32 v[116:117], 0
	v_mov_b64_e32 v[118:119], 0
	v_mov_b64_e32 v[120:121], 0
	v_mov_b64_e32 v[122:123], 0
	v_mov_b64_e32 v[124:125], 0
	v_mov_b64_e32 v[126:127], 0
	s_addc_u32 s53, s69, 0
	s_mov_b32 s54, -2
	s_and_b64 vcc, exec, s[14:15]
	s_cbranch_vccnz .Lsp_skip_6
	s_setprio 1

; template <class Epi, class Sched, bool ALIGN_EPI = false, bool SP2 = false>
; __device__ __forceinline__ void gemm_phase(PG8_LAS unsigned char* lds, const Gemm g, const Sched& S, const Epi& E) {
;     ...
;         for (int a = 0; a < 2; ++a)
; #pragma unroll
;             for (int b = 0; b < 2; ++b)
; #pragma unroll
;                 for (int m = 0; m < 4; ++m)
; #pragma unroll
;                     for (int n = 0; n < 2; ++n) acc[a][b][m][n] = (f32x4){0.f, 0.f, 0.f, 0.f};
.LBB0_307:
	s_add_u32 s10, s14, 0x160080
	s_addc_u32 s11, s15, 0
	s_add_u32 s17, s12, 0x100
	v_mov_b64_e32 v[0:1], 0
	v_mov_b64_e32 v[2:3], 0
	v_mov_b64_e32 v[4:5], 0
	v_mov_b64_e32 v[6:7], 0
	v_mov_b64_e32 v[8:9], 0
	v_mov_b64_e32 v[10:11], 0
	v_mov_b64_e32 v[12:13], 0
	v_mov_b64_e32 v[14:15], 0
	v_mov_b64_e32 v[16:17], 0
	v_mov_b64_e32 v[18:19], 0
	v_mov_b64_e32 v[20:21], 0
	v_mov_b64_e32 v[22:23], 0
	v_mov_b64_e32 v[24:25], 0
	v_mov_b64_e32 v[26:27], 0
	v_mov_b64_e32 v[28:29], 0
	v_mov_b64_e32 v[30:31], 0
	v_mov_b64_e32 v[32:33], 0
	v_mov_b64_e32 v[34:35], 0
	v_mov_b64_e32 v[36:37], 0
	v_mov_b64_e32 v[38:39], 0
	v_mov_b64_e32 v[40:41], 0
	v_mov_b64_e32 v[42:43], 0
	v_mov_b64_e32 v[44:45], 0
	v_mov_b64_e32 v[46:47], 0
	v_mov_b64_e32 v[48:49], 0
	v_mov_b64_e32 v[50:51], 0
	v_mov_b64_e32 v[52:53], 0
	v_mov_b64_e32 v[54:55], 0
	v_mov_b64_e32 v[56:57], 0
	v_mov_b64_e32 v[58:59], 0
	v_mov_b64_e32 v[60:61], 0
	v_mov_b64_e32 v[62:63], 0
	v_mov_b64_e32 v[64:65], 0
	v_mov_b64_e32 v[66:67], 0
	v_mov_b64_e32 v[68:69], 0
	v_mov_b64_e32 v[70:71], 0
	v_mov_b64_e32 v[72:73], 0
	v_mov_b64_e32 v[74:75], 0
	v_mov_b64_e32 v[76:77], 0
	v_mov_b64_e32 v[78:79], 0
	v_mov_b64_e32 v[80:81], 0
	v_mov_b64_e32 v[82:83], 0
	v_mov_b64_e32 v[84:85], 0
	v_mov_b64_e32 v[86:87], 0
	v_mov_b64_e32 v[88:89], 0
	v_mov_b64_e32 v[90:91], 0
	v_mov_b64_e32 v[92:93], 0
	v_mov_b64_e32 v[94:95], 0
	v_mov_b64_e32 v[96:97], 0
	v_mov_b64_e32 v[98:99], 0
	v_mov_b64_e32 v[100:101], 0
	v_mov_b64_e32 v[102:103], 0
	v_mov_b64_e32 v[104:105], 0
	v_mov_b64_e32 v[106:107], 0
	v_mov_b64_e32 v[108:109], 0
	v_mov_b64_e32 v[110:111], 0
	v_mov_b64_e32 v[112:113], 0
	v_mov_b64_e32 v[114:115], 0
	v_mov_b64_e32 v[116:117], 0
	v_mov_b64_e32 v[118:119], 0
	v_mov_b64_e32 v[120:121], 0
	v_mov_b64_e32 v[122:123], 0
	v_mov_b64_e32 v[124:125], 0
	v_mov_b64_e32 v[126:127], 0
	s_addc_u32 s39, s13, 0
	s_mov_b32 s40, -2
	s_waitcnt lgkmcnt(0)
	s_and_b64 vcc, exec, s[74:75]
	s_cbranch_vccnz .Lsp_skip_5
	s_setprio 1

;     __device__ __forceinline__ bool next(int i, Unit& u) const { if (i > 0 || c >= nitems) return false; u.pm = 64; u.pn = c % npn; u.k0 = (c / npn) * kslice; return true; }
; template <class Epi, class Sched, bool ALIGN_EPI = false, bool SP2 = false>
; __device__ __forceinline__ void gemm_phase(PG8_LAS unsigned char* lds, const Gemm g, const Sched& S, const Epi& E) {
;     ...
;         const bool has_next = S.next(ui + 1, nxt);
;         const char* nA = has_next ? (const char*)g.A + (size_t)nxt.pm * tstep + (size_t)nxt.k0 * 2 : cA; const char* nB = has_next ? (const char*)g.Bt + (size_t)nxt.pn * tstep + (size_t)nxt.k0 * 2 : cB;
;     ...
;         for (int a = 0; a < 2; ++a)
; #pragma unroll
;             for (int b = 0; b < 2; ++b)
; #pragma unroll
;                 for (int m = 0; m < 4; ++m)
; #pragma unroll
;                     for (int n = 0; n < 2; ++n) acc[a][b][m][n] = (f32x4){0.f, 0.f, 0.f, 0.f};
.LBB0_622:
	s_ashr_i32 s71, s70, 31
	s_lshl_b64 s[36:37], s[70:71], 20
	s_add_u32 s72, s33, s36
	s_addc_u32 s73, s82, s37
	s_and_b64 s[36:37], s[8:9], exec
	s_cselect_b32 s36, s73, s11
	s_cselect_b32 s37, s72, s10
	s_ashr_i32 s69, s68, 31
	s_lshl_b64 s[38:39], s[68:69], 20
	s_add_u32 s74, s83, s38
	s_addc_u32 s75, s84, s39
	s_and_b64 s[38:39], s[8:9], exec
	s_cselect_b32 s38, s75, s77
	s_cselect_b32 s39, s74, s76
	s_add_u32 s10, s10, 0x80080
	s_addc_u32 s11, s11, 0
	s_add_u32 s40, s76, 0x100
	v_mov_b64_e32 v[0:1], 0
	v_mov_b64_e32 v[2:3], 0
	v_mov_b64_e32 v[4:5], 0
	v_mov_b64_e32 v[6:7], 0
	v_mov_b64_e32 v[8:9], 0
	v_mov_b64_e32 v[10:11], 0
	v_mov_b64_e32 v[12:13], 0
	v_mov_b64_e32 v[14:15], 0
	v_mov_b64_e32 v[16:17], 0
	v_mov_b64_e32 v[18:19], 0
	v_mov_b64_e32 v[20:21], 0
	v_mov_b64_e32 v[22:23], 0
	v_mov_b64_e32 v[24:25], 0
	v_mov_b64_e32 v[26:27], 0
	v_mov_b64_e32 v[28:29], 0
	v_mov_b64_e32 v[30:31], 0
	v_mov_b64_e32 v[32:33], 0
	v_mov_b64_e32 v[34:35], 0
	v_mov_b64_e32 v[36:37], 0
	v_mov_b64_e32 v[38:39], 0
	v_mov_b64_e32 v[40:41], 0
	v_mov_b64_e32 v[42:43], 0
	v_mov_b64_e32 v[44:45], 0
	v_mov_b64_e32 v[46:47], 0
	v_mov_b64_e32 v[48:49], 0
	v_mov_b64_e32 v[50:51], 0
	v_mov_b64_e32 v[52:53], 0
	v_mov_b64_e32 v[54:55], 0
	v_mov_b64_e32 v[56:57], 0
	v_mov_b64_e32 v[58:59], 0
	v_mov_b64_e32 v[60:61], 0
	v_mov_b64_e32 v[62:63], 0
	v_mov_b64_e32 v[64:65], 0
	v_mov_b64_e32 v[66:67], 0
	v_mov_b64_e32 v[68:69], 0
	v_mov_b64_e32 v[70:71], 0
	v_mov_b64_e32 v[72:73], 0
	v_mov_b64_e32 v[74:75], 0
	v_mov_b64_e32 v[76:77], 0
	v_mov_b64_e32 v[78:79], 0
	v_mov_b64_e32 v[80:81], 0
	v_mov_b64_e32 v[82:83], 0
	v_mov_b64_e32 v[84:85], 0
	v_mov_b64_e32 v[86:87], 0
	v_mov_b64_e32 v[88:89], 0
	v_mov_b64_e32 v[90:91], 0
	v_mov_b64_e32 v[92:93], 0
	v_mov_b64_e32 v[94:95], 0
	v_mov_b64_e32 v[96:97], 0
	v_mov_b64_e32 v[98:99], 0
	v_mov_b64_e32 v[100:101], 0
	v_mov_b64_e32 v[102:103], 0
	v_mov_b64_e32 v[104:105], 0
	v_mov_b64_e32 v[106:107], 0
	v_mov_b64_e32 v[108:109], 0
	v_mov_b64_e32 v[110:111], 0
	v_mov_b64_e32 v[112:113], 0
	v_mov_b64_e32 v[114:115], 0
	v_mov_b64_e32 v[116:117], 0
	v_mov_b64_e32 v[118:119], 0
	v_mov_b64_e32 v[120:121], 0
	v_mov_b64_e32 v[122:123], 0
	v_mov_b64_e32 v[124:125], 0
	v_mov_b64_e32 v[126:127], 0
	s_addc_u32 s41, s77, 0
	s_mov_b32 s42, -2
	s_and_b64 vcc, exec, s[66:67]
	s_cbranch_vccnz .Lsp_skip_4
	s_setprio 1

;     __device__ __forceinline__ bool next(int i, Unit& u) const { if (i > 0 || c >= nitems) return false; u.pm = 64; u.pn = c % npn; u.k0 = (c / npn) * kslice; return true; }
; template <class Epi, class Sched, bool ALIGN_EPI = false, bool SP2 = false>
; __device__ __forceinline__ void gemm_phase(PG8_LAS unsigned char* lds, const Gemm g, const Sched& S, const Epi& E) {
;     ...
;         const bool has_next = S.next(ui + 1, nxt);
;         const char* nA = has_next ? (const char*)g.A + (size_t)nxt.pm * tstep + (size_t)nxt.k0 * 2 : cA; const char* nB = has_next ? (const char*)g.Bt + (size_t)nxt.pn * tstep + (size_t)nxt.k0 * 2 : cB;
;     ...
;         for (int a = 0; a < 2; ++a)
; #pragma unroll
;             for (int b = 0; b < 2; ++b)
; #pragma unroll
;                 for (int m = 0; m < 4; ++m)
; #pragma unroll
;                     for (int n = 0; n < 2; ++n) acc[a][b][m][n] = (f32x4){0.f, 0.f, 0.f, 0.f};
.LBB0_1055:
	s_ashr_i32 s27, s26, 31
	s_lshl_b64 s[28:29], s[26:27], 20
	s_add_u32 s28, s33, s28
	s_addc_u32 s29, s44, s29
	s_and_b64 s[30:31], s[10:11], exec
	s_cselect_b32 s27, s29, s39
	s_cselect_b32 s35, s28, s38
	s_ashr_i32 s25, s24, 31
	s_lshl_b64 s[30:31], s[24:25], 20
	s_add_u32 s30, s2, s30
	s_addc_u32 s31, s3, s31
	s_and_b64 s[42:43], s[10:11], exec
	s_cselect_b32 s25, s31, s41
	s_cselect_b32 s37, s30, s40
	s_add_u32 s38, s38, 0x80080
	s_addc_u32 s39, s39, 0
	s_add_u32 s63, s40, 0x100
	v_mov_b64_e32 v[0:1], 0
	v_mov_b64_e32 v[2:3], 0
	v_mov_b64_e32 v[4:5], 0
	v_mov_b64_e32 v[6:7], 0
	v_mov_b64_e32 v[8:9], 0
	v_mov_b64_e32 v[10:11], 0
	v_mov_b64_e32 v[12:13], 0
	v_mov_b64_e32 v[14:15], 0
	v_mov_b64_e32 v[16:17], 0
	v_mov_b64_e32 v[18:19], 0
	v_mov_b64_e32 v[20:21], 0
	v_mov_b64_e32 v[22:23], 0
	v_mov_b64_e32 v[24:25], 0
	v_mov_b64_e32 v[26:27], 0
	v_mov_b64_e32 v[28:29], 0
	v_mov_b64_e32 v[30:31], 0
	v_mov_b64_e32 v[32:33], 0
	v_mov_b64_e32 v[34:35], 0
	v_mov_b64_e32 v[36:37], 0
	v_mov_b64_e32 v[38:39], 0
	v_mov_b64_e32 v[40:41], 0
	v_mov_b64_e32 v[42:43], 0
	v_mov_b64_e32 v[44:45], 0
	v_mov_b64_e32 v[46:47], 0
	v_mov_b64_e32 v[48:49], 0
	v_mov_b64_e32 v[50:51], 0
	v_mov_b64_e32 v[52:53], 0
	v_mov_b64_e32 v[54:55], 0
	v_mov_b64_e32 v[56:57], 0
	v_mov_b64_e32 v[58:59], 0
	v_mov_b64_e32 v[60:61], 0
	v_mov_b64_e32 v[62:63], 0
	v_mov_b64_e32 v[64:65], 0
	v_mov_b64_e32 v[66:67], 0
	v_mov_b64_e32 v[68:69], 0
	v_mov_b64_e32 v[70:71], 0
	v_mov_b64_e32 v[72:73], 0
	v_mov_b64_e32 v[74:75], 0
	v_mov_b64_e32 v[76:77], 0
	v_mov_b64_e32 v[78:79], 0
	v_mov_b64_e32 v[80:81], 0
	v_mov_b64_e32 v[82:83], 0
	v_mov_b64_e32 v[84:85], 0
	v_mov_b64_e32 v[86:87], 0
	v_mov_b64_e32 v[88:89], 0
	v_mov_b64_e32 v[90:91], 0
	v_mov_b64_e32 v[92:93], 0
	v_mov_b64_e32 v[94:95], 0
	v_mov_b64_e32 v[96:97], 0
	v_mov_b64_e32 v[98:99], 0
	v_mov_b64_e32 v[100:101], 0
	v_mov_b64_e32 v[102:103], 0
	v_mov_b64_e32 v[104:105], 0
	v_mov_b64_e32 v[106:107], 0
	v_mov_b64_e32 v[108:109], 0
	v_mov_b64_e32 v[110:111], 0
	v_mov_b64_e32 v[112:113], 0
	v_mov_b64_e32 v[114:115], 0
	v_mov_b64_e32 v[116:117], 0
	v_mov_b64_e32 v[118:119], 0
	v_mov_b64_e32 v[120:121], 0
	v_mov_b64_e32 v[122:123], 0
	v_mov_b64_e32 v[124:125], 0
	v_mov_b64_e32 v[126:127], 0
	s_addc_u32 s64, s41, 0
	s_mov_b32 s65, -2
	s_waitcnt lgkmcnt(0)
	s_and_b64 vcc, exec, s[22:23]
	s_cbranch_vccnz .Lsp_skip_3
	s_setprio 1

;     __device__ __forceinline__ bool next(int i, Unit& u) const { if (i > 0 || c >= nitems) return false; u.pm = 64; u.pn = c % npn; u.k0 = (c / npn) * kslice; return true; }
; template <class Epi, class Sched, bool ALIGN_EPI = false, bool SP2 = false>
; __device__ __forceinline__ void gemm_phase(PG8_LAS unsigned char* lds, const Gemm g, const Sched& S, const Epi& E) {
;     ...
;         const bool has_next = S.next(ui + 1, nxt);
;         const char* nA = has_next ? (const char*)g.A + (size_t)nxt.pm * tstep + (size_t)nxt.k0 * 2 : cA; const char* nB = has_next ? (const char*)g.Bt + (size_t)nxt.pn * tstep + (size_t)nxt.k0 * 2 : cB;
;     ...
;         for (int a = 0; a < 2; ++a)
; #pragma unroll
;             for (int b = 0; b < 2; ++b)
; #pragma unroll
;                 for (int m = 0; m < 4; ++m)
; #pragma unroll
;                     for (int n = 0; n < 2; ++n) acc[a][b][m][n] = (f32x4){0.f, 0.f, 0.f, 0.f};
.LBB0_1278:
	s_ashr_i32 s21, s20, 31
	s_lshl_b64 s[22:23], s[20:21], 20
	s_add_u32 s22, s3, s22
	s_addc_u32 s23, s33, s23
	s_and_b64 s[24:25], s[6:7], exec
	s_cselect_b32 s21, s23, s27
	s_cselect_b32 s50, s22, s26
	s_ashr_i32 s19, s18, 31
	s_lshl_b64 s[24:25], s[18:19], 20
	s_add_u32 s24, s34, s24
	s_addc_u32 s25, s35, s25
	s_and_b64 s[30:31], s[6:7], exec
	s_cselect_b32 s19, s25, s29
	s_cselect_b32 s51, s24, s28
	s_add_u32 s26, s26, 0x80080
	s_addc_u32 s27, s27, 0
	s_add_u32 s52, s28, 0x100
	v_mov_b64_e32 v[0:1], 0
	v_mov_b64_e32 v[2:3], 0
	v_mov_b64_e32 v[4:5], 0
	v_mov_b64_e32 v[6:7], 0
	v_mov_b64_e32 v[8:9], 0
	v_mov_b64_e32 v[10:11], 0
	v_mov_b64_e32 v[12:13], 0
	v_mov_b64_e32 v[14:15], 0
	v_mov_b64_e32 v[16:17], 0
	v_mov_b64_e32 v[18:19], 0
	v_mov_b64_e32 v[20:21], 0
	v_mov_b64_e32 v[22:23], 0
	v_mov_b64_e32 v[24:25], 0
	v_mov_b64_e32 v[26:27], 0
	v_mov_b64_e32 v[28:29], 0
	v_mov_b64_e32 v[30:31], 0
	v_mov_b64_e32 v[32:33], 0
	v_mov_b64_e32 v[34:35], 0
	v_mov_b64_e32 v[36:37], 0
	v_mov_b64_e32 v[38:39], 0
	v_mov_b64_e32 v[40:41], 0
	v_mov_b64_e32 v[42:43], 0
	v_mov_b64_e32 v[44:45], 0
	v_mov_b64_e32 v[46:47], 0
	v_mov_b64_e32 v[48:49], 0
	v_mov_b64_e32 v[50:51], 0
	v_mov_b64_e32 v[52:53], 0
	v_mov_b64_e32 v[54:55], 0
	v_mov_b64_e32 v[56:57], 0
	v_mov_b64_e32 v[58:59], 0
	v_mov_b64_e32 v[60:61], 0
	v_mov_b64_e32 v[62:63], 0
	v_mov_b64_e32 v[64:65], 0
	v_mov_b64_e32 v[66:67], 0
	v_mov_b64_e32 v[68:69], 0
	v_mov_b64_e32 v[70:71], 0
	v_mov_b64_e32 v[72:73], 0
	v_mov_b64_e32 v[74:75], 0
	v_mov_b64_e32 v[76:77], 0
	v_mov_b64_e32 v[78:79], 0
	v_mov_b64_e32 v[80:81], 0
	v_mov_b64_e32 v[82:83], 0
	v_mov_b64_e32 v[84:85], 0
	v_mov_b64_e32 v[86:87], 0
	v_mov_b64_e32 v[88:89], 0
	v_mov_b64_e32 v[90:91], 0
	v_mov_b64_e32 v[92:93], 0
	v_mov_b64_e32 v[94:95], 0
	v_mov_b64_e32 v[96:97], 0
	v_mov_b64_e32 v[98:99], 0
	v_mov_b64_e32 v[100:101], 0
	v_mov_b64_e32 v[102:103], 0
	v_mov_b64_e32 v[104:105], 0
	v_mov_b64_e32 v[106:107], 0
	v_mov_b64_e32 v[108:109], 0
	v_mov_b64_e32 v[110:111], 0
	v_mov_b64_e32 v[112:113], 0
	v_mov_b64_e32 v[114:115], 0
	v_mov_b64_e32 v[116:117], 0
	v_mov_b64_e32 v[118:119], 0
	v_mov_b64_e32 v[120:121], 0
	v_mov_b64_e32 v[122:123], 0
	v_mov_b64_e32 v[124:125], 0
	v_mov_b64_e32 v[126:127], 0
	s_addc_u32 s53, s29, 0
	s_mov_b32 s54, -2
	s_and_b64 vcc, exec, s[16:17]
	s_cbranch_vccnz .Lsp_skip_2
	s_setprio 1

; template <class Epi, class Sched, bool ALIGN_EPI = false, bool SP2 = false>
; __device__ __forceinline__ void gemm_phase(PG8_LAS unsigned char* lds, const Gemm g, const Sched& S, const Epi& E) {
;     ...
;         for (int a = 0; a < 2; ++a)
; #pragma unroll
;             for (int b = 0; b < 2; ++b)
; #pragma unroll
;                 for (int m = 0; m < 4; ++m)
; #pragma unroll
;                     for (int n = 0; n < 2; ++n) acc[a][b][m][n] = (f32x4){0.f, 0.f, 0.f, 0.f};
.LBB0_1360:
	s_add_u32 s20, s20, 0x160080
	s_addc_u32 s21, s21, 0
	s_add_u32 s53, s22, 0x100
	v_mov_b64_e32 v[0:1], 0
	v_mov_b64_e32 v[2:3], 0
	v_mov_b64_e32 v[4:5], 0
	v_mov_b64_e32 v[6:7], 0
	v_mov_b64_e32 v[8:9], 0
	v_mov_b64_e32 v[10:11], 0
	v_mov_b64_e32 v[12:13], 0
	v_mov_b64_e32 v[14:15], 0
	v_mov_b64_e32 v[16:17], 0
	v_mov_b64_e32 v[18:19], 0
	v_mov_b64_e32 v[20:21], 0
	v_mov_b64_e32 v[22:23], 0
	v_mov_b64_e32 v[24:25], 0
	v_mov_b64_e32 v[26:27], 0
	v_mov_b64_e32 v[28:29], 0
	v_mov_b64_e32 v[30:31], 0
	v_mov_b64_e32 v[32:33], 0
	v_mov_b64_e32 v[34:35], 0
	v_mov_b64_e32 v[36:37], 0
	v_mov_b64_e32 v[38:39], 0
	v_mov_b64_e32 v[40:41], 0
	v_mov_b64_e32 v[42:43], 0
	v_mov_b64_e32 v[44:45], 0
	v_mov_b64_e32 v[46:47], 0
	v_mov_b64_e32 v[48:49], 0
	v_mov_b64_e32 v[50:51], 0
	v_mov_b64_e32 v[52:53], 0
	v_mov_b64_e32 v[54:55], 0
	v_mov_b64_e32 v[56:57], 0
	v_mov_b64_e32 v[58:59], 0
	v_mov_b64_e32 v[60:61], 0
	v_mov_b64_e32 v[62:63], 0
	v_mov_b64_e32 v[64:65], 0
	v_mov_b64_e32 v[66:67], 0
	v_mov_b64_e32 v[68:69], 0
	v_mov_b64_e32 v[70:71], 0
	v_mov_b64_e32 v[72:73], 0
	v_mov_b64_e32 v[74:75], 0
	v_mov_b64_e32 v[76:77], 0
	v_mov_b64_e32 v[78:79], 0
	v_mov_b64_e32 v[80:81], 0
	v_mov_b64_e32 v[82:83], 0
	v_mov_b64_e32 v[84:85], 0
	v_mov_b64_e32 v[86:87], 0
	v_mov_b64_e32 v[88:89], 0
	v_mov_b64_e32 v[90:91], 0
	v_mov_b64_e32 v[92:93], 0
	v_mov_b64_e32 v[94:95], 0
	v_mov_b64_e32 v[96:97], 0
	v_mov_b64_e32 v[98:99], 0
	v_mov_b64_e32 v[100:101], 0
	v_mov_b64_e32 v[102:103], 0
	v_mov_b64_e32 v[104:105], 0
	v_mov_b64_e32 v[106:107], 0
	v_mov_b64_e32 v[108:109], 0
	v_mov_b64_e32 v[110:111], 0
	v_mov_b64_e32 v[112:113], 0
	v_mov_b64_e32 v[114:115], 0
	v_mov_b64_e32 v[116:117], 0
	v_mov_b64_e32 v[118:119], 0
	v_mov_b64_e32 v[120:121], 0
	v_mov_b64_e32 v[122:123], 0
	v_mov_b64_e32 v[124:125], 0
	v_mov_b64_e32 v[126:127], 0
	s_addc_u32 s54, s23, 0
	s_mov_b32 s55, -2
	s_and_b64 vcc, exec, s[16:17]
	s_cbranch_vccnz .Lsp_skip_1
	s_setprio 1
